# MLA QK rolling prefetch started from the first MFMA (6 reads up front instead of 8), FoX K rolling prefetch
# speedup vs baseline: 1.0614x; 1.0027x over previous
; #define LAS __attribute__((address_space(3)))
; template <int DQK, int DV, bool FOX> ...
;     ...
;                 for (int g0 = 0; g0 < ND0; g0 += GB) { bf16x8 ka[GB], kb[GB];
; #pragma unroll
;                     for (int j = 0; j < GB; ++j) { const int c = 2 * (g0 + j) + h; const int co = ((c & ~7) | ((c ^ ksw) & 7)) * 16;
;                         ka[j] = *(const LAS bf16x8*)(b + kread0 + co); kb[j] = *(const LAS bf16x8*)(b + kread0 + 32 * KROW + co); }
;                     __builtin_amdgcn_sched_barrier(0);
; #pragma unroll
;                     for (int j = 0; j < GB; ++j) { p0 = __builtin_amdgcn_mfma_f32_32x32x16_bf16(ka[j], qf[g0 + j], p0, 0, 0, 0);
;                                                    p1 = __builtin_amdgcn_mfma_f32_32x32x16_bf16(kb[j], qf[g0 + j], p1, 0, 0, 0); }
;                     __builtin_amdgcn_sched_barrier(0); } }
;     ...
;             float rm = fmaxf(fmaxf(p0[0], p1[0]), p0[1]);
; #pragma unroll
;             for (int i = 1; i < 15; ++i) rm = fmaxf(fmaxf(rm, p1[i]), p0[i + 1]);
;             rm = fmaxf(rm, p1[15]);
;             { const auto rr_ = __builtin_amdgcn_permlane32_swap(__float_as_uint(rm), __float_as_uint(rm), false, false);
;               rm = fmaxf(__uint_as_float(rr_[0]), __uint_as_float(rr_[1])); }
;             const bool grow = rm > mloc + THR;
;             if (__any(grow)) {
;                 const float mnew = grow ? rm : mloc; const float al = __builtin_amdgcn_exp2f(mloc - mnew);
;                 lsum *= al; mref = grow ? (mnew + cqt) : mref; mloc = mnew;
;                 if (h == 0) wsf[r] = al;
;                 asm volatile("s_waitcnt lgkmcnt(0)" ::: "memory");
; #pragma unroll
;                 for (int g = 0; g < 4; ++g) { const f32x4 a4 = *(const LAS f32x4*)(wsf + 8 * g + 4 * h);
; #pragma unroll
;                     for (int cb = 0; cb < NCB; ++cb)
; #pragma unroll
;                         for (int e = 0; e < 4; ++e) o[cb][4 * g + e] *= a4[e]; }
.LBB0_723:
	s_mul_i32 s1, s6, 0xa100
	s_add_i32 s1, s1, 0
	v_mul_u32_u24_e32 v66, 0x180, v146
	v_add_u32_e32 v193, s1, v66
	v_add_u32_e32 v195, v193, v197
	v_add_u32_e32 v210, v193, v211
	v_add_u32_e32 v254, v193, v212
	v_add_u32_e32 v193, v193, v213
	ds_read_b128 v[66:69], v195
	ds_read_b128 v[70:73], v195 offset:12288
	ds_read_b128 v[234:237], v210
	ds_read_b128 v[238:241], v210 offset:12288
	ds_read_b128 v[242:245], v254
	ds_read_b128 v[246:249], v254 offset:12288
	s_waitcnt lgkmcnt(5)
	v_mfma_f32_32x32x16_bf16 v[82:97], v[66:69], v[98:101], 0
	ds_read_b128 v[250:253], v193
	s_waitcnt lgkmcnt(5)
	v_mfma_f32_32x32x16_bf16 v[66:81], v[70:73], v[98:101], 0
	ds_read_b128 v[214:217], v193 offset:12288
	s_waitcnt lgkmcnt(5)
	v_mfma_f32_32x32x16_bf16 v[82:97], v[234:237], v[102:105], v[82:97]
	ds_read_b128 v[234:237], v195 offset:128
	s_waitcnt lgkmcnt(5)
	v_mfma_f32_32x32x16_bf16 v[66:81], v[238:241], v[102:105], v[66:81]
	ds_read_b128 v[238:241], v195 offset:12416
	s_waitcnt lgkmcnt(5)
	v_mfma_f32_32x32x16_bf16 v[82:97], v[242:245], v[106:109], v[82:97]
	ds_read_b128 v[242:245], v210 offset:128
	s_waitcnt lgkmcnt(5)
	v_mfma_f32_32x32x16_bf16 v[66:81], v[246:249], v[106:109], v[66:81]
	ds_read_b128 v[246:249], v210 offset:12416
	s_waitcnt lgkmcnt(5)
	v_mfma_f32_32x32x16_bf16 v[82:97], v[250:253], v[110:113], v[82:97]
	ds_read_b128 v[250:253], v254 offset:128
	s_waitcnt lgkmcnt(5)
	v_mfma_f32_32x32x16_bf16 v[66:81], v[214:217], v[110:113], v[66:81]
	ds_read_b128 v[214:217], v254 offset:12416
	s_waitcnt lgkmcnt(5)
	v_mfma_f32_32x32x16_bf16 v[82:97], v[234:237], v[114:117], v[82:97]
	ds_read_b128 v[234:237], v193 offset:128
	s_waitcnt lgkmcnt(5)
	v_mfma_f32_32x32x16_bf16 v[66:81], v[238:241], v[114:117], v[66:81]
	ds_read_b128 v[238:241], v193 offset:12416
	s_waitcnt lgkmcnt(5)
	v_mfma_f32_32x32x16_bf16 v[82:97], v[242:245], v[118:121], v[82:97]
	ds_read_b128 v[242:245], v195 offset:256
	s_waitcnt lgkmcnt(5)
	v_mfma_f32_32x32x16_bf16 v[66:81], v[246:249], v[118:121], v[66:81]
	ds_read_b128 v[246:249], v195 offset:12544
	s_waitcnt lgkmcnt(5)
	v_mfma_f32_32x32x16_bf16 v[82:97], v[250:253], v[122:125], v[82:97]
	ds_read_b128 v[250:253], v210 offset:256
	s_waitcnt lgkmcnt(5)
	v_mfma_f32_32x32x16_bf16 v[66:81], v[214:217], v[122:125], v[66:81]
	ds_read_b128 v[214:217], v210 offset:12544
	s_waitcnt lgkmcnt(5)
	v_mfma_f32_32x32x16_bf16 v[82:97], v[234:237], v[126:129], v[82:97]
	ds_read_b128 v[234:237], v254 offset:256
	s_waitcnt lgkmcnt(5)
	v_mfma_f32_32x32x16_bf16 v[66:81], v[238:241], v[126:129], v[66:81]
	ds_read_b128 v[238:241], v254 offset:12544
	s_waitcnt lgkmcnt(5)
	v_mfma_f32_32x32x16_bf16 v[82:97], v[242:245], v[130:133], v[82:97]
	ds_read_b128 v[242:245], v193 offset:256
	s_waitcnt lgkmcnt(5)
	v_mfma_f32_32x32x16_bf16 v[66:81], v[246:249], v[130:133], v[66:81]
	ds_read_b128 v[246:249], v193 offset:12544
	s_waitcnt lgkmcnt(5)
	v_mfma_f32_32x32x16_bf16 v[82:97], v[250:253], v[134:137], v[82:97]
	s_waitcnt lgkmcnt(4)
	v_mfma_f32_32x32x16_bf16 v[66:81], v[214:217], v[134:137], v[66:81]
	s_waitcnt lgkmcnt(3)
	v_mfma_f32_32x32x16_bf16 v[82:97], v[234:237], v[138:141], v[82:97]
	s_waitcnt lgkmcnt(2)
	v_mfma_f32_32x32x16_bf16 v[66:81], v[238:241], v[138:141], v[66:81]
	s_waitcnt lgkmcnt(1)
	v_mfma_f32_32x32x16_bf16 v[82:97], v[242:245], v[142:145], v[82:97]
	s_waitcnt lgkmcnt(0)
	v_mfma_f32_32x32x16_bf16 v[66:81], v[246:249], v[142:145], v[66:81]
	s_nop 11
	v_max_f32_e32 v193, v66, v66
	v_max_f32_e32 v195, v82, v82
	v_max_f32_e32 v193, v195, v193
	v_max3_f32 v193, v193, v83, v67
	v_max3_f32 v193, v193, v84, v68
	v_max3_f32 v193, v193, v85, v69
	v_max3_f32 v193, v193, v86, v70
	v_max3_f32 v193, v193, v87, v71
	v_max3_f32 v193, v193, v88, v72
	v_max3_f32 v193, v193, v89, v73
	v_max3_f32 v193, v193, v90, v74
	v_max3_f32 v193, v193, v91, v75
	v_max3_f32 v193, v193, v92, v76
	v_max3_f32 v193, v193, v93, v77
	v_max3_f32 v193, v193, v94, v78
	v_max3_f32 v193, v193, v95, v79
	v_max3_f32 v193, v193, v96, v80
	v_max3_f32 v193, v193, v97, v81
	v_mov_b32_e32 v195, v193
	s_nop 1
	v_permlane32_swap_b32_e32 v193, v195
	v_max_f32_e32 v195, v195, v195
	v_max_f32_e32 v193, v193, v193
	v_max_f32_e32 v193, v193, v195
	v_add_f32_e32 v195, 0x40c00000, v233
	v_cmp_gt_f32_e32 vcc, v193, v195
	s_cbranch_vccz .LBB0_727
	s_nop 0
	v_cndmask_b32_e32 v210, v233, v193, vcc
	v_sub_f32_e32 v195, v233, v210
	v_exp_f32_e32 v195, v195
	s_and_saveexec_b64 s[2:3], s[12:13]
	ds_write_b32 v231, v195
	s_or_b64 exec, exec, s[2:3]
	s_waitcnt lgkmcnt(0)
	ds_read_b128 v[214:217], v230 offset:64
	ds_read_b128 v[234:237], v230 offset:96
	ds_read_b128 v[238:241], v230
	ds_read_b128 v[242:245], v230 offset:32
	v_add_f32_e32 v193, 0, v193
	v_mul_f32_e32 v232, v232, v195
	v_cndmask_b32_e32 v233, v233, v193, vcc
	s_waitcnt lgkmcnt(2)
	v_pk_mul_f32 v[64:65], v[64:65], v[236:237]
	v_pk_mul_f32 v[60:61], v[60:61], v[216:217]
	s_waitcnt lgkmcnt(0)
	v_pk_mul_f32 v[56:57], v[56:57], v[244:245]
	v_pk_mul_f32 v[52:53], v[52:53], v[240:241]
	v_pk_mul_f32 v[62:63], v[62:63], v[234:235]
	v_pk_mul_f32 v[58:59], v[58:59], v[214:215]
	v_pk_mul_f32 v[54:55], v[54:55], v[242:243]
	v_pk_mul_f32 v[50:51], v[50:51], v[238:239]
	v_pk_mul_f32 v[48:49], v[48:49], v[236:237]
	v_pk_mul_f32 v[44:45], v[44:45], v[216:217]
	v_pk_mul_f32 v[40:41], v[40:41], v[244:245]
	v_pk_mul_f32 v[36:37], v[36:37], v[240:241]
	v_pk_mul_f32 v[46:47], v[46:47], v[234:235]
	v_pk_mul_f32 v[42:43], v[42:43], v[214:215]
	v_pk_mul_f32 v[38:39], v[38:39], v[242:243]
	v_pk_mul_f32 v[34:35], v[34:35], v[238:239]
	v_pk_mul_f32 v[32:33], v[32:33], v[236:237]
	v_pk_mul_f32 v[28:29], v[28:29], v[216:217]
	v_pk_mul_f32 v[24:25], v[24:25], v[244:245]
	v_pk_mul_f32 v[20:21], v[20:21], v[240:241]
	v_pk_mul_f32 v[30:31], v[30:31], v[234:235]
	v_pk_mul_f32 v[26:27], v[26:27], v[214:215]
	v_pk_mul_f32 v[22:23], v[22:23], v[242:243]
	v_pk_mul_f32 v[18:19], v[18:19], v[238:239]
	v_pk_mul_f32 v[16:17], v[16:17], v[236:237]
	v_pk_mul_f32 v[12:13], v[12:13], v[216:217]
	v_pk_mul_f32 v[8:9], v[8:9], v[244:245]
	v_pk_mul_f32 v[4:5], v[4:5], v[240:241]
	v_pk_mul_f32 v[14:15], v[14:15], v[234:235]
	v_pk_mul_f32 v[10:11], v[10:11], v[214:215]
	v_pk_mul_f32 v[6:7], v[6:7], v[242:243]
	v_pk_mul_f32 v[2:3], v[2:3], v[238:239]
	s_branch .LBB0_728
